# combo10: combo8 with s_sleep removed from the barrier poll loops
# speedup vs baseline: 1.0042x; 1.0042x over previous
; __device__ __forceinline__ unsigned xb_ld(unsigned* p)              { return __hip_atomic_load(p, __ATOMIC_RELAXED, __HIP_MEMORY_SCOPE_AGENT); }
; #define XB_SPIN(cond, bar) do { unsigned _sp = 0; while (cond) { __builtin_amdgcn_s_sleep(1); \
;     if ((++_sp & 255u) == 0u) { if (xb_ld(&(bar)[XB_TMO])) break; if (_sp > XB_SPIN_CAP) { atomicAdd(&(bar)[XB_TMO], 1u); break; } } } } while (0)
; __device__ __forceinline__ void xcd_barrier(const XcdBarrier& b) {
;     ...
;             XB_SPIN(xb_ld(&bar[XB_XGEN(b.x)]) == gen, bar);
.LBB0_96:
	s_and_b32 s18, s22, 0xff
	s_mov_b64 s[16:17], -1
	s_cmp_lg_u32 s18, 0
	s_mov_b64 s[20:21], -1
	s_nop 0
	s_cbranch_scc1 .LBB0_99
	global_load_dword v2, v0, s[8:9] sc1
	s_waitcnt vmcnt(0)
	v_cmp_eq_u32_e32 vcc, 0, v2
	s_cbranch_vccnz .LBB0_101
	s_mov_b64 s[20:21], 0
	s_mov_b64 s[18:19], -1

; __device__ __forceinline__ unsigned xb_ld(unsigned* p)              { return __hip_atomic_load(p, __ATOMIC_RELAXED, __HIP_MEMORY_SCOPE_AGENT); }
; #define XB_SPIN(cond, bar) do { unsigned _sp = 0; while (cond) { __builtin_amdgcn_s_sleep(1); \
;     if ((++_sp & 255u) == 0u) { if (xb_ld(&(bar)[XB_TMO])) break; if (_sp > XB_SPIN_CAP) { atomicAdd(&(bar)[XB_TMO], 1u); break; } } } } while (0)
; __device__ __forceinline__ void xcd_barrier(const XcdBarrier& b) {
;     ...
;             else XB_SPIN(xb_ld(&bar[XB_TOPGEN]) == tg, bar);
.LBB0_113:
	s_and_b32 s16, s22, 0xff
	s_cmp_lg_u32 s16, 0
	s_mov_b64 s[18:19], -1
	s_nop 0
	s_cbranch_scc1 .LBB0_116
	global_load_dword v1, v0, s[8:9] sc1
	s_waitcnt vmcnt(0)
	v_cmp_eq_u32_e32 vcc, 0, v1
	s_cbranch_vccnz .LBB0_118
	s_mov_b64 s[18:19], 0
	s_mov_b64 s[16:17], -1
